# odd in-proj GEMM epilogue: raw bf16 output stored 16 bytes per lane (v_permlane16_swap pairs), two stores per 16-row group instead of four
# speedup vs baseline: 1.0176x; 1.0024x over previous
; #define MFMA16(a, b, c) __builtin_amdgcn_mfma_f32_16x16x32_bf16((a), (b), (c), 0, 0, 0)
; template <class Epi>
; DEVI void gemm_tile256b(const bf16_t* __restrict__ A, int lda, const bf16_t* __restrict__ Bt, int K,
;                         int m0, int n0, char* smem, Epi epi) {
;     ...
;   for (int kt = 0; kt < nk; ++kt) {
;     const char* base = smem + (kt & 1) * 32768;
;     const bool more = kt + 1 < nk;
;     if (more) {
; #pragma unroll
;       for (int i = 0; i < 8; ++i) ra[i] = *(const u32x4*)(ag + (size_t)(i * 32) * lda + (kt + 1) * 64);
;     }
; #pragma unroll
;     for (int i = 0; i < 4; ++i) b1[i] = *(const bf16x8*)(bp + ((size_t)i * kb32 + kt * 2 + 1) * 512);
;     {
;       bf16x8 af[8];
; #pragma unroll
;       for (int i = 0; i < 8; ++i) af[i] = *(const bf16x8*)(base + a_rd + i * 2048);
; #pragma unroll
;       for (int mi = 0; mi < 8; ++mi)
; #pragma unroll
;         for (int ni = 0; ni < 4; ++ni) acc[mi][ni] = MFMA16(b0[ni], af[mi], acc[mi][ni]);
;     }
;     if (more) {
; #pragma unroll
;       for (int i = 0; i < 4; ++i) b0[i] = *(const bf16x8*)(bp + ((size_t)i * kb32 + kt * 2 + 2) * 512);
;     }
;     {
;       bf16x8 af[8];
; #pragma unroll
;       for (int i = 0; i < 8; ++i) af[i] = *(const bf16x8*)(base + ((a_rd + i * 2048) ^ 64));
; #pragma unroll
;       for (int mi = 0; mi < 8; ++mi)
; #pragma unroll
;         for (int ni = 0; ni < 4; ++ni) acc[mi][ni] = MFMA16(b1[ni], af[mi], acc[mi][ni]);
;     }
;     if (more) {
;       char* nb = smem + ((kt + 1) & 1) * 32768 + lds_w;
; #pragma unroll
;       for (int i = 0; i < 8; ++i) *(u32x4*)(nb + i * 4096) = ra[i];
;     }
;     __syncthreads();
.LBB0_1367:
	s_add_i32 s10, s1, 0xffff8000
	s_and_b32 s10, s10, 0x8000
	s_add_i32 s10, s10, 32
	v_add_u32_e32 v0, s10, v173
	ds_read_b128 v[146:149], v0
	ds_read_b128 v[150:153], v0 offset:2048
	v_lshl_add_u64 v[154:155], v[164:165], 0, s[28:29]
	v_add_co_u32_e32 v156, vcc, s11, v154
	s_waitcnt vmcnt(3) lgkmcnt(1)
	v_mfma_f32_16x16x32_bf16 v[130:133], v[2:5], v[146:149], v[130:133]
	v_addc_co_u32_e32 v157, vcc, 0, v155, vcc
	v_add_co_u32_e32 v158, vcc, s13, v154
	s_waitcnt vmcnt(2)
	v_mfma_f32_16x16x32_bf16 v[126:129], v[14:17], v[146:149], v[126:129]
	v_addc_co_u32_e32 v159, vcc, 0, v155, vcc
	v_add_co_u32_e32 v160, vcc, s16, v154
	s_waitcnt vmcnt(1)
	v_mfma_f32_16x16x32_bf16 v[122:125], v[10:13], v[146:149], v[122:125]
	v_addc_co_u32_e32 v161, vcc, 0, v155, vcc
	v_add_co_u32_e32 v182, vcc, s17, v154
	s_waitcnt vmcnt(0)
	v_mfma_f32_16x16x32_bf16 v[118:121], v[6:9], v[146:149], v[118:121]
	v_addc_co_u32_e32 v183, vcc, 0, v155, vcc
	s_waitcnt lgkmcnt(0)
	v_mfma_f32_16x16x32_bf16 v[114:117], v[2:5], v[150:153], v[114:117]
	v_lshl_add_u64 v[164:165], v[164:165], 0, s[64:65]
	v_mfma_f32_16x16x32_bf16 v[106:109], v[14:17], v[150:153], v[106:109]
	v_mfma_f32_16x16x32_bf16 v[102:105], v[10:13], v[150:153], v[102:105]
	s_nop 0
	v_mfma_f32_16x16x32_bf16 v[98:101], v[6:9], v[150:153], v[98:101]
	ds_read_b128 v[146:149], v0 offset:4096
	ds_read_b128 v[150:153], v0 offset:6144
	s_waitcnt lgkmcnt(1)
	v_mfma_f32_16x16x32_bf16 v[94:97], v[2:5], v[146:149], v[94:97]
	v_lshl_add_u64 v[166:167], v[166:167], 0, s[60:61]
	v_mfma_f32_16x16x32_bf16 v[86:89], v[14:17], v[146:149], v[86:89]
	v_mfma_f32_16x16x32_bf16 v[82:85], v[10:13], v[146:149], v[82:85]
	s_nop 0
	v_mfma_f32_16x16x32_bf16 v[78:81], v[6:9], v[146:149], v[78:81]
	s_nop 0
	s_waitcnt lgkmcnt(0)
	v_mfma_f32_16x16x32_bf16 v[74:77], v[2:5], v[150:153], v[74:77]
	v_mfma_f32_16x16x32_bf16 v[70:73], v[14:17], v[150:153], v[70:73]
	v_mfma_f32_16x16x32_bf16 v[62:65], v[10:13], v[150:153], v[62:65]
	v_mfma_f32_16x16x32_bf16 v[66:69], v[6:9], v[150:153], v[66:69]
	ds_read_b128 v[146:149], v0 offset:8192
	ds_read_b128 v[150:153], v0 offset:10240
	s_waitcnt lgkmcnt(1)
	v_mfma_f32_16x16x32_bf16 v[46:49], v[2:5], v[146:149], v[46:49]
	v_mfma_f32_16x16x32_bf16 v[50:53], v[14:17], v[146:149], v[50:53]
	v_mfma_f32_16x16x32_bf16 v[58:61], v[10:13], v[146:149], v[58:61]
	v_mfma_f32_16x16x32_bf16 v[54:57], v[6:9], v[146:149], v[54:57]
	s_waitcnt lgkmcnt(0)
	v_mfma_f32_16x16x32_bf16 v[26:29], v[2:5], v[150:153], v[26:29]
	v_mfma_f32_16x16x32_bf16 v[22:25], v[14:17], v[150:153], v[22:25]
	v_mfma_f32_16x16x32_bf16 v[18:21], v[10:13], v[150:153], v[18:21]
	v_mfma_f32_16x16x32_bf16 v[42:45], v[6:9], v[150:153], v[42:45]
	ds_read_b128 v[146:149], v0 offset:12288
	ds_read_b128 v[150:153], v0 offset:14336
	v_add_u32_e32 v0, s10, v171
	s_and_b32 s10, s1, 0x8000
	s_waitcnt lgkmcnt(1)
	v_mfma_f32_16x16x32_bf16 v[30:33], v[2:5], v[146:149], v[30:33]
	s_add_i32 s1, s1, 0x8000
	s_cmp_eq_u32 s1, 0x80000
	v_mfma_f32_16x16x32_bf16 v[38:41], v[14:17], v[146:149], v[38:41]
	v_mfma_f32_16x16x32_bf16 v[34:37], v[10:13], v[146:149], v[34:37]
	v_mfma_f32_16x16x32_bf16 v[142:145], v[6:9], v[146:149], v[142:145]
	global_load_dwordx4 v[146:149], v[156:157], off offset:1024
	ds_read_b128 v[174:177], v0
	ds_read_b128 v[178:181], v0 offset:2048
	s_waitcnt lgkmcnt(2)
	v_mfma_f32_16x16x32_bf16 v[138:141], v[2:5], v[150:153], v[138:141]
	global_load_dwordx4 v[2:5], v[156:157], off offset:2048
	v_mfma_f32_16x16x32_bf16 v[134:137], v[14:17], v[150:153], v[134:137]
	v_mfma_f32_16x16x32_bf16 v[110:113], v[10:13], v[150:153], v[110:113]
	v_mfma_f32_16x16x32_bf16 v[90:93], v[6:9], v[150:153], v[90:93]
	global_load_dwordx4 v[150:153], v[158:159], off offset:1024
	global_load_dwordx4 v[14:17], v[158:159], off offset:2048
	global_load_dwordx4 v[154:157], v[160:161], off offset:1024
	global_load_dwordx4 v[10:13], v[160:161], off offset:2048
	s_nop 0
	global_load_dwordx4 v[158:161], v[182:183], off offset:1024
	global_load_dwordx4 v[6:9], v[182:183], off offset:2048
	v_lshrrev_b32_e32 v195, 6, v206
	v_lshl_add_u64 v[190:191], v[166:167], 0, s[28:29]
	v_lshrrev_b32_e32 v194, 3, v206
	v_readfirstlane_b32 s99, v195
	v_and_b32_e32 v194, 7, v194
	s_and_b32 s98, s1, 0x8000
	s_xor_b32 s98, s98, 0x8000
	v_lshlrev_b32_e32 v194, 4, v194
	s_lshl_b32 s99, s99, 10
	v_xor_b32_e32 v190, v194, v190
	s_add_u32 s98, s98, s99
	s_add_u32 s98, s98, 32
	s_mov_b32 s101, 0
	s_mov_b32 s100, 0x0
	v_lshl_add_u64 v[192:193], v[190:191], 0, s[100:101]
	s_mov_b32 m0, s98
	s_nop 0
	global_load_lds_dwordx4 v[192:193], off
	s_add_u32 s100, s54, 0x0
	v_lshl_add_u64 v[192:193], v[190:191], 0, s[100:101]
	s_add_u32 m0, s98, 0x1000
	s_nop 0
	global_load_lds_dwordx4 v[192:193], off
	s_add_u32 s100, s53, 0x0
	v_lshl_add_u64 v[192:193], v[190:191], 0, s[100:101]
	s_add_u32 m0, s98, 0x2000
	s_nop 0
	global_load_lds_dwordx4 v[192:193], off
	s_add_u32 s100, s52, 0x0
	v_lshl_add_u64 v[192:193], v[190:191], 0, s[100:101]
	s_add_u32 m0, s98, 0x3000
	s_nop 0
	global_load_lds_dwordx4 v[192:193], off
	s_add_u32 s100, s56, 0x0
	v_lshl_add_u64 v[192:193], v[190:191], 0, s[100:101]
	s_add_u32 m0, s98, 0x4000
	s_nop 0
	global_load_lds_dwordx4 v[192:193], off
	s_add_u32 s100, s57, 0x0
	v_lshl_add_u64 v[192:193], v[190:191], 0, s[100:101]
	s_add_u32 m0, s98, 0x5000
	s_nop 0
	global_load_lds_dwordx4 v[192:193], off
	s_add_u32 s100, s3, 0x0
	v_lshl_add_u64 v[192:193], v[190:191], 0, s[100:101]
	s_add_u32 m0, s98, 0x6000
	s_nop 0
	global_load_lds_dwordx4 v[192:193], off
	s_add_u32 s100, s19, 0x0
	v_lshl_add_u64 v[192:193], v[190:191], 0, s[100:101]
	s_add_u32 m0, s98, 0x7000
	s_nop 0
	global_load_lds_dwordx4 v[192:193], off
	s_waitcnt vmcnt(15) lgkmcnt(1)
; #define MFMA16(a, b, c) __builtin_amdgcn_mfma_f32_16x16x32_bf16((a), (b), (c), 0, 0, 0)
; template <class Epi>
; DEVI void gemm_tile256b(const bf16_t* __restrict__ A, int lda, const bf16_t* __restrict__ Bt, int K,
;                         int m0, int n0, char* smem, Epi epi) {
;     ...
;     {
;       bf16x8 af[8];
; #pragma unroll
;       for (int i = 0; i < 8; ++i) af[i] = *(const bf16x8*)(base + ((a_rd + i * 2048) ^ 64));
; #pragma unroll
;       for (int mi = 0; mi < 8; ++mi)
; #pragma unroll
;         for (int ni = 0; ni < 4; ++ni) acc[mi][ni] = MFMA16(b1[ni], af[mi], acc[mi][ni]);
;     }
;     if (more) {
;       char* nb = smem + ((kt + 1) & 1) * 32768 + lds_w;
; #pragma unroll
;       for (int i = 0; i < 8; ++i) *(u32x4*)(nb + i * 4096) = ra[i];
;     }
;     __syncthreads();
;   }
; #pragma unroll
;   for (int mi = 0; mi < 8; ++mi)
; #pragma unroll
;     for (int ni = 0; ni < 4; ++ni)
;       epi(m0 + wm * 128 + mi * 16 + l15, n0 + wn * 64 + ni * 16 + quad * 4, acc[mi][ni]);
	v_mfma_f32_16x16x32_bf16 v[130:133], v[146:149], v[174:177], v[130:133]
	s_waitcnt vmcnt(13)
	v_mfma_f32_16x16x32_bf16 v[126:129], v[150:153], v[174:177], v[126:129]
	s_waitcnt vmcnt(11)
	v_mfma_f32_16x16x32_bf16 v[122:125], v[154:157], v[174:177], v[122:125]
	s_waitcnt vmcnt(9)
	v_mfma_f32_16x16x32_bf16 v[118:121], v[158:161], v[174:177], v[118:121]
	s_waitcnt lgkmcnt(0)
	v_mfma_f32_16x16x32_bf16 v[114:117], v[146:149], v[178:181], v[114:117]
	v_mfma_f32_16x16x32_bf16 v[106:109], v[150:153], v[178:181], v[106:109]
	v_mfma_f32_16x16x32_bf16 v[102:105], v[154:157], v[178:181], v[102:105]
	v_mfma_f32_16x16x32_bf16 v[98:101], v[158:161], v[178:181], v[98:101]
	ds_read_b128 v[174:177], v0 offset:4096
	ds_read_b128 v[178:181], v0 offset:6144
	s_waitcnt lgkmcnt(1)
	v_mfma_f32_16x16x32_bf16 v[94:97], v[146:149], v[174:177], v[94:97]
	v_mfma_f32_16x16x32_bf16 v[86:89], v[150:153], v[174:177], v[86:89]
	v_mfma_f32_16x16x32_bf16 v[82:85], v[154:157], v[174:177], v[82:85]
	v_mfma_f32_16x16x32_bf16 v[78:81], v[158:161], v[174:177], v[78:81]
	s_waitcnt lgkmcnt(0)
	v_mfma_f32_16x16x32_bf16 v[74:77], v[146:149], v[178:181], v[74:77]
	v_mfma_f32_16x16x32_bf16 v[70:73], v[150:153], v[178:181], v[70:73]
	v_mfma_f32_16x16x32_bf16 v[62:65], v[154:157], v[178:181], v[62:65]
	v_mfma_f32_16x16x32_bf16 v[66:69], v[158:161], v[178:181], v[66:69]
	ds_read_b128 v[178:181], v0 offset:8192
	ds_read_b128 v[182:185], v0 offset:10240
	s_waitcnt lgkmcnt(1)
	v_mfma_f32_16x16x32_bf16 v[46:49], v[146:149], v[178:181], v[46:49]
	v_mfma_f32_16x16x32_bf16 v[50:53], v[150:153], v[178:181], v[50:53]
	v_mfma_f32_16x16x32_bf16 v[58:61], v[154:157], v[178:181], v[58:61]
	v_mfma_f32_16x16x32_bf16 v[54:57], v[158:161], v[178:181], v[54:57]
	s_waitcnt lgkmcnt(0)
	v_mfma_f32_16x16x32_bf16 v[26:29], v[146:149], v[182:185], v[26:29]
	v_mfma_f32_16x16x32_bf16 v[22:25], v[150:153], v[182:185], v[22:25]
	v_mfma_f32_16x16x32_bf16 v[18:21], v[154:157], v[182:185], v[18:21]
	v_mfma_f32_16x16x32_bf16 v[42:45], v[158:161], v[182:185], v[42:45]
	ds_read_b128 v[178:181], v0 offset:12288
	ds_read_b128 v[182:185], v0 offset:14336
	s_nop 0
	s_nop 0
	s_nop 0
	s_nop 0
	s_nop 0
	s_waitcnt lgkmcnt(1)
	v_mfma_f32_16x16x32_bf16 v[30:33], v[146:149], v[178:181], v[30:33]
	v_mfma_f32_16x16x32_bf16 v[38:41], v[150:153], v[178:181], v[38:41]
	v_mfma_f32_16x16x32_bf16 v[34:37], v[154:157], v[178:181], v[34:37]
	s_waitcnt vmcnt(0) lgkmcnt(0)
	s_barrier
	v_mfma_f32_16x16x32_bf16 v[142:145], v[158:161], v[178:181], v[142:145]
	v_mfma_f32_16x16x32_bf16 v[138:141], v[146:149], v[182:185], v[138:141]
	v_mfma_f32_16x16x32_bf16 v[134:137], v[150:153], v[182:185], v[134:137]
	v_mfma_f32_16x16x32_bf16 v[110:113], v[154:157], v[182:185], v[110:113]
	v_mfma_f32_16x16x32_bf16 v[90:93], v[158:161], v[182:185], v[90:93]
	s_cmp_eq_u32 s1, 0x80000
	s_cbranch_scc0 .LBB0_1367
	v_and_b32_e32 v228, 16, v206
	v_lshrrev_b32_e32 v229, 1, v228
	v_add_u32_e32 v228, v228, v229
	v_mov_b32_e32 v229, 0
	v_add_u32_e32 v0, 32, v173
	ds_read_b128 v[146:149], v0 offset:32768
	s_movk_i32 s1, 0x7000
	s_movk_i32 s10, 0x1800
	s_waitcnt lgkmcnt(0)
	v_mfma_f32_16x16x32_bf16 v[130:133], v[2:5], v[146:149], v[130:133]
	v_mfma_f32_16x16x32_bf16 v[150:153], v[14:17], v[146:149], v[126:129]
	v_mfma_f32_16x16x32_bf16 v[154:157], v[10:13], v[146:149], v[122:125]
	v_mfma_f32_16x16x32_bf16 v[146:149], v[6:9], v[146:149], v[118:121]
	s_nop 2
	ds_read_b128 v[118:121], v0 offset:34816
	s_waitcnt lgkmcnt(0)
	v_mfma_f32_16x16x32_bf16 v[158:161], v[2:5], v[118:121], v[114:117]
	s_nop 2
	ds_read_b128 v[114:117], v0 offset:36864
	s_waitcnt lgkmcnt(0)
	v_mfma_f32_16x16x32_bf16 v[94:97], v[2:5], v[114:117], v[94:97]
	v_mfma_f32_16x16x32_bf16 v[86:89], v[14:17], v[114:117], v[86:89]
	v_mfma_f32_16x16x32_bf16 v[82:85], v[10:13], v[114:117], v[82:85]
	v_mfma_f32_16x16x32_bf16 v[78:81], v[6:9], v[114:117], v[78:81]
	ds_read_b128 v[114:117], v0 offset:38912
	s_waitcnt lgkmcnt(0)
	v_mfma_f32_16x16x32_bf16 v[74:77], v[2:5], v[114:117], v[74:77]
	v_mfma_f32_16x16x32_bf16 v[70:73], v[14:17], v[114:117], v[70:73]
	v_mfma_f32_16x16x32_bf16 v[62:65], v[10:13], v[114:117], v[62:65]
	v_mfma_f32_16x16x32_bf16 v[66:69], v[6:9], v[114:117], v[66:69]
	ds_read_b128 v[114:117], v0 offset:40960
	s_waitcnt lgkmcnt(0)
	v_mfma_f32_16x16x32_bf16 v[172:175], v[6:9], v[114:117], v[54:57]
	s_nop 2
	ds_read_b128 v[54:57], v0 offset:43008
	s_waitcnt lgkmcnt(0)
	v_mfma_f32_16x16x32_bf16 v[176:179], v[6:9], v[54:57], v[42:45]
	s_nop 2
	ds_read_b128 v[42:45], v0 offset:45056
	s_waitcnt lgkmcnt(0)
	v_mfma_f32_16x16x32_bf16 v[190:193], v[10:13], v[42:45], v[34:37]
	s_nop 2
	ds_read_b128 v[34:37], v0 offset:47104
	v_add_u32_e32 v0, 32, v171
	v_mfma_f32_16x16x32_bf16 v[106:109], v[14:17], v[118:121], v[106:109]
	v_mfma_f32_16x16x32_bf16 v[50:53], v[14:17], v[114:117], v[50:53]
	v_mfma_f32_16x16x32_bf16 v[22:25], v[14:17], v[54:57], v[22:25]
	v_mfma_f32_16x16x32_bf16 v[180:183], v[14:17], v[42:45], v[38:41]
	s_waitcnt lgkmcnt(0)
; #define MFMA16(a, b, c) __builtin_amdgcn_mfma_f32_16x16x32_bf16((a), (b), (c), 0, 0, 0)
; template <class Epi>
; DEVI void gemm_tile256b(const bf16_t* __restrict__ A, int lda, const bf16_t* __restrict__ Bt, int K,
;                         int m0, int n0, char* smem, Epi epi) {
;     ...
;     {
;       bf16x8 af[8];
; #pragma unroll
;       for (int i = 0; i < 8; ++i) af[i] = *(const bf16x8*)(base + ((a_rd + i * 2048) ^ 64));
; #pragma unroll
;       for (int mi = 0; mi < 8; ++mi)
; #pragma unroll
;         for (int ni = 0; ni < 4; ++ni) acc[mi][ni] = MFMA16(b1[ni], af[mi], acc[mi][ni]);
;     }
;     if (more) {
;       char* nb = smem + ((kt + 1) & 1) * 32768 + lds_w;
; #pragma unroll
;       for (int i = 0; i < 8; ++i) *(u32x4*)(nb + i * 4096) = ra[i];
;     }
;     __syncthreads();
;   }
; #pragma unroll
;   for (int mi = 0; mi < 8; ++mi)
; #pragma unroll
;     for (int ni = 0; ni < 4; ++ni)
;       epi(m0 + wm * 128 + mi * 16 + l15, n0 + wn * 64 + ni * 16 + quad * 4, acc[mi][ni]);
;   DEVI void operator()(int m, int n, f32x4 v) const {
;     if (m >= L) return;
;     if (n < 3072) {
;       *(u32x2*)(raw + (size_t)m * 3072 + n) = u32x2{pack2(v[0], v[1]), pack2(v[2], v[3])};
;     } else if (n < 3088) {
;       *(f32x4*)(ba + (size_t)m * 16 + (n - 3072)) = v;
;     }
;   }
	v_mfma_f32_16x16x32_bf16 v[134:137], v[14:17], v[34:37], v[134:137]
	v_add_co_u32_e32 v14, vcc, s1, v162
	s_mov_b32 s1, 0xf000
	s_nop 0
	v_addc_co_u32_e32 v15, vcc, 0, v163, vcc
	v_mfma_f32_16x16x32_bf16 v[102:105], v[10:13], v[118:121], v[102:105]
	global_load_dwordx4 v[14:17], v[14:15], off offset:3072
	v_mfma_f32_16x16x32_bf16 v[46:49], v[2:5], v[114:117], v[46:49]
	v_mfma_f32_16x16x32_bf16 v[164:167], v[10:13], v[114:117], v[58:61]
	v_mfma_f32_16x16x32_bf16 v[26:29], v[2:5], v[54:57], v[26:29]
	v_mfma_f32_16x16x32_bf16 v[18:21], v[10:13], v[54:57], v[18:21]
	v_mfma_f32_16x16x32_bf16 v[30:33], v[2:5], v[42:45], v[30:33]
	v_mfma_f32_16x16x32_bf16 v[2:5], v[2:5], v[34:37], v[138:141]
	v_mfma_f32_16x16x32_bf16 v[138:141], v[10:13], v[34:37], v[110:113]
	v_add_co_u32_e32 v10, vcc, s1, v162
	s_mov_b32 s1, 0x17000
	s_nop 0
	v_addc_co_u32_e32 v11, vcc, 0, v163, vcc
	global_load_dwordx4 v[10:13], v[10:11], off offset:3072
	v_mfma_f32_16x16x32_bf16 v[98:101], v[6:9], v[118:121], v[98:101]
	v_mfma_f32_16x16x32_bf16 v[142:145], v[6:9], v[42:45], v[142:145]
	v_mfma_f32_16x16x32_bf16 v[194:197], v[6:9], v[34:37], v[90:93]
	ds_read_b128 v[6:9], v0 offset:32768
	v_add_co_u32_e32 v34, vcc, s1, v162
	s_mov_b32 s1, 0x1f000
	s_nop 0
	v_addc_co_u32_e32 v35, vcc, 0, v163, vcc
	global_load_dwordx4 v[198:201], v[34:35], off offset:3072
	v_add_co_u32_e32 v34, vcc, s1, v162
	s_waitcnt vmcnt(1) lgkmcnt(0)
	v_mfma_f32_16x16x32_bf16 v[122:125], v[10:13], v[6:9], v[150:153]
	v_addc_co_u32_e32 v35, vcc, 0, v163, vcc
	s_nop 1
	global_load_dwordx4 v[150:153], v[34:35], off offset:3072
	v_mfma_f32_16x16x32_bf16 v[126:129], v[14:17], v[6:9], v[130:133]
	s_waitcnt vmcnt(1)
	v_mfma_f32_16x16x32_bf16 v[118:121], v[198:201], v[6:9], v[154:157]
	s_nop 0
	v_lshl_or_b32 v130, v170, 2, v168
	s_waitcnt vmcnt(0)
	v_mfma_f32_16x16x32_bf16 v[114:117], v[150:153], v[6:9], v[146:149]
	ds_read_b128 v[6:9], v0 offset:34816
	s_nop 1
	ds_read_b128 v[146:149], v0 offset:47104
	s_waitcnt lgkmcnt(1)
	v_mfma_f32_16x16x32_bf16 v[110:113], v[14:17], v[6:9], v[158:161]
	v_mfma_f32_16x16x32_bf16 v[106:109], v[10:13], v[6:9], v[106:109]
	v_mfma_f32_16x16x32_bf16 v[102:105], v[198:201], v[6:9], v[102:105]
	v_mfma_f32_16x16x32_bf16 v[98:101], v[150:153], v[6:9], v[98:101]
	ds_read_b128 v[6:9], v0 offset:36864
	s_waitcnt lgkmcnt(0)
	v_mfma_f32_16x16x32_bf16 v[94:97], v[14:17], v[6:9], v[94:97]
	v_mfma_f32_16x16x32_bf16 v[90:93], v[10:13], v[6:9], v[86:89]
	v_mfma_f32_16x16x32_bf16 v[86:89], v[198:201], v[6:9], v[82:85]
	v_mfma_f32_16x16x32_bf16 v[82:85], v[150:153], v[6:9], v[78:81]
	ds_read_b128 v[6:9], v0 offset:38912
	s_waitcnt lgkmcnt(0)
	v_mfma_f32_16x16x32_bf16 v[78:81], v[14:17], v[6:9], v[74:77]
	v_mfma_f32_16x16x32_bf16 v[74:77], v[10:13], v[6:9], v[70:73]
	v_mfma_f32_16x16x32_bf16 v[70:73], v[198:201], v[6:9], v[62:65]
	v_mfma_f32_16x16x32_bf16 v[66:69], v[150:153], v[6:9], v[66:69]
	ds_read_b128 v[6:9], v0 offset:40960
	s_waitcnt lgkmcnt(0)
	v_mfma_f32_16x16x32_bf16 v[62:65], v[14:17], v[6:9], v[46:49]
	v_mfma_f32_16x16x32_bf16 v[58:61], v[10:13], v[6:9], v[50:53]
	v_mfma_f32_16x16x32_bf16 v[54:57], v[198:201], v[6:9], v[164:167]
	v_mfma_f32_16x16x32_bf16 v[50:53], v[150:153], v[6:9], v[172:175]
	ds_read_b128 v[6:9], v0 offset:43008
	s_waitcnt lgkmcnt(0)
	v_mfma_f32_16x16x32_bf16 v[46:49], v[14:17], v[6:9], v[26:29]
	v_mfma_f32_16x16x32_bf16 v[42:45], v[10:13], v[6:9], v[22:25]
	v_mfma_f32_16x16x32_bf16 v[38:41], v[198:201], v[6:9], v[18:21]
	v_mfma_f32_16x16x32_bf16 v[34:37], v[150:153], v[6:9], v[176:179]
	ds_read_b128 v[6:9], v0 offset:45056
	v_and_b32_e32 v0, 0xffffff80, v169
	v_add_u32_e32 v0, s0, v0
	v_and_or_b32 v132, v169, 15, v0
	v_ashrrev_i32_e32 v133, 31, v132
	s_waitcnt lgkmcnt(0)
	v_mfma_f32_16x16x32_bf16 v[30:33], v[14:17], v[6:9], v[30:33]
	s_movk_i32 s0, 0x4010
	v_cmp_gt_i32_e64 s[0:1], s0, v132
	v_mfma_f32_16x16x32_bf16 v[14:17], v[14:17], v[146:149], v[2:5]
	s_barrier
	s_nop 1
	v_lshlrev_b64 v[2:3], 6, v[132:133]
	v_mfma_f32_16x16x32_bf16 v[26:29], v[10:13], v[6:9], v[180:183]
	v_mfma_f32_16x16x32_bf16 v[10:13], v[10:13], v[146:149], v[134:137]
	s_nop 2
	v_lshl_add_u64 v[136:137], s[6:7], 0, v[2:3]
	v_mov_b64_e32 v[2:3], s[30:31]
	v_mfma_f32_16x16x32_bf16 v[22:25], v[198:201], v[6:9], v[190:193]
	v_mad_i64_i32 v[134:135], s[10:11], v132, s10, v[2:3]
	v_mfma_f32_16x16x32_bf16 v[18:21], v[150:153], v[6:9], v[142:145]
	v_mfma_f32_16x16x32_bf16 v[6:9], v[198:201], v[146:149], v[138:141]
	v_mfma_f32_16x16x32_bf16 v[2:5], v[150:153], v[146:149], v[194:197]
	s_and_saveexec_b64 s[10:11], s[0:1]
	s_cbranch_execz .LBB0_1375
	s_movk_i32 s13, 0xbff
	v_cmp_lt_i32_e32 vcc, s13, v130
	s_and_saveexec_b64 s[16:17], vcc
	s_xor_b64 s[16:17], exec, s[16:17]
	s_cbranch_execz .LBB0_1373
	s_movk_i32 s13, 0xc10
	v_cmp_gt_u32_e32 vcc, s13, v168
	s_and_saveexec_b64 s[34:35], vcc
	s_cbranch_execz .LBB0_1372
	v_mov_b32_e32 v131, v1
	v_lshl_add_u64 v[138:139], v[130:131], 2, v[136:137]
	v_add_co_u32_e32 v138, vcc, 0xffffd000, v138
	s_nop 1
	v_addc_co_u32_e32 v139, vcc, -1, v139, vcc
	global_store_dwordx4 v[138:139], v[126:129], off

;   DEVI void operator()(int m, int n, f32x4 v) const {
;     if (m >= L) return;
;     if (n < 3072) {
;       *(u32x2*)(raw + (size_t)m * 3072 + n) = u32x2{pack2(v[0], v[1]), pack2(v[2], v[3])};
.LBB0_1373:
	s_andn2_saveexec_b64 s[16:17], s[16:17]
	s_cbranch_execz .LBB0_1375
	v_ashrrev_i32_e32 v131, 31, v130
	v_cvt_pk_bf16_f32 v230, v126, v127
	v_cvt_pk_bf16_f32 v231, v128, v129

;   DEVI void operator()(int m, int n, f32x4 v) const {
;     if (m >= L) return;
;     if (n < 3072) {
;       *(u32x2*)(raw + (size_t)m * 3072 + n) = u32x2{pack2(v[0], v[1]), pack2(v[2], v[3])};
.LBB0_1380:
	s_andn2_saveexec_b64 s[16:17], s[16:17]
	s_cbranch_execz .LBB0_1382
	v_ashrrev_i32_e32 v131, 31, v130
	v_cvt_pk_bf16_f32 v232, v122, v123
	v_cvt_pk_bf16_f32 v233, v124, v125
	v_lshl_add_u64 v[226:227], v[130:131], 1, v[134:135]
	v_lshl_add_u64 v[226:227], v[226:227], 0, v[228:229]
	s_nop 0
	v_permlane16_swap_b32_e32 v230, v232
	v_permlane16_swap_b32_e32 v231, v233
	global_store_dwordx4 v[226:227], v[230:233], off
	s_nop 1

;   DEVI void operator()(int m, int n, f32x4 v) const {
;     if (m >= L) return;
;     if (n < 3072) {
;       *(u32x2*)(raw + (size_t)m * 3072 + n) = u32x2{pack2(v[0], v[1]), pack2(v[2], v[3])};
.LBB0_1387:
	s_andn2_saveexec_b64 s[16:17], s[16:17]
	s_cbranch_execz .LBB0_1389
	v_ashrrev_i32_e32 v131, 31, v130
	v_cvt_pk_bf16_f32 v230, v118, v119
	v_cvt_pk_bf16_f32 v231, v120, v121

;   DEVI void operator()(int m, int n, f32x4 v) const {
;     if (m >= L) return;
;     if (n < 3072) {
;       *(u32x2*)(raw + (size_t)m * 3072 + n) = u32x2{pack2(v[0], v[1]), pack2(v[2], v[3])};
.LBB0_1394:
	s_andn2_saveexec_b64 s[0:1], s[0:1]
	s_cbranch_execz .LBB0_1396
	v_ashrrev_i32_e32 v131, 31, v130
	v_cvt_pk_bf16_f32 v232, v114, v115
	v_cvt_pk_bf16_f32 v233, v116, v117
	v_lshl_add_u64 v[226:227], v[130:131], 1, v[134:135]
	v_lshl_add_u64 v[226:227], v[226:227], 0, v[228:229]
	s_nop 0
	v_permlane16_swap_b32_e32 v230, v232
	v_permlane16_swap_b32_e32 v231, v233
	global_store_dwordx4 v[226:227], v[230:233], off offset:64
	s_nop 1

;   DEVI void operator()(int m, int n, f32x4 v) const {
;     if (m >= L) return;
;     if (n < 3072) {
;       *(u32x2*)(raw + (size_t)m * 3072 + n) = u32x2{pack2(v[0], v[1]), pack2(v[2], v[3])};
.LBB0_1401:
	s_or_saveexec_b64 s[10:11], s[10:11]
	v_mov_b64_e32 v[120:121], s[30:31]
	s_movk_i32 s13, 0x1800
	v_mad_i64_i32 v[116:117], s[16:17], v116, s13, v[120:121]
	s_xor_b64 exec, exec, s[10:11]
	s_cbranch_execz .LBB0_1403
	v_ashrrev_i32_e32 v131, 31, v130
	v_cvt_pk_bf16_f32 v230, v110, v111
	v_cvt_pk_bf16_f32 v231, v112, v113

;   DEVI void operator()(int m, int n, f32x4 v) const {
;     if (m >= L) return;
;     if (n < 3072) {
;       *(u32x2*)(raw + (size_t)m * 3072 + n) = u32x2{pack2(v[0], v[1]), pack2(v[2], v[3])};
.LBB0_1407:
	s_andn2_saveexec_b64 s[10:11], s[10:11]
	s_cbranch_execz .LBB0_1409
	v_ashrrev_i32_e32 v131, 31, v130
	v_cvt_pk_bf16_f32 v232, v106, v107
	v_cvt_pk_bf16_f32 v233, v108, v109
	v_lshl_add_u64 v[226:227], v[130:131], 1, v[116:117]
	v_lshl_add_u64 v[226:227], v[226:227], 0, v[228:229]
	s_nop 0
	v_permlane16_swap_b32_e32 v230, v232
	v_permlane16_swap_b32_e32 v231, v233
	global_store_dwordx4 v[226:227], v[230:233], off
	s_nop 1

;   DEVI void operator()(int m, int n, f32x4 v) const {
;     if (m >= L) return;
;     if (n < 3072) {
;       *(u32x2*)(raw + (size_t)m * 3072 + n) = u32x2{pack2(v[0], v[1]), pack2(v[2], v[3])};
.LBB0_1413:
	s_andn2_saveexec_b64 s[10:11], s[10:11]
	s_cbranch_execz .LBB0_1415
	v_ashrrev_i32_e32 v131, 31, v130
	v_cvt_pk_bf16_f32 v230, v102, v103
	v_cvt_pk_bf16_f32 v231, v104, v105

;   DEVI void operator()(int m, int n, f32x4 v) const {
;     if (m >= L) return;
;     if (n < 3072) {
;       *(u32x2*)(raw + (size_t)m * 3072 + n) = u32x2{pack2(v[0], v[1]), pack2(v[2], v[3])};
.LBB0_1419:
	s_andn2_saveexec_b64 s[10:11], s[10:11]
	s_cbranch_execz .LBB0_1421
	v_ashrrev_i32_e32 v131, 31, v130
	v_cvt_pk_bf16_f32 v232, v98, v99
	v_cvt_pk_bf16_f32 v233, v100, v101
	v_lshl_add_u64 v[226:227], v[130:131], 1, v[116:117]
	v_lshl_add_u64 v[226:227], v[226:227], 0, v[228:229]
	s_nop 0
	v_permlane16_swap_b32_e32 v230, v232
	v_permlane16_swap_b32_e32 v231, v233
	global_store_dwordx4 v[226:227], v[230:233], off offset:64
	s_nop 1

;   DEVI void operator()(int m, int n, f32x4 v) const {
;     if (m >= L) return;
;     if (n < 3072) {
;       *(u32x2*)(raw + (size_t)m * 3072 + n) = u32x2{pack2(v[0], v[1]), pack2(v[2], v[3])};
.LBB0_1426:
	s_or_saveexec_b64 s[10:11], s[10:11]
	v_mov_b64_e32 v[102:103], s[30:31]
	s_movk_i32 s13, 0x1800
	v_mad_i64_i32 v[100:101], s[16:17], v100, s13, v[102:103]
	s_xor_b64 exec, exec, s[10:11]
	s_cbranch_execz .LBB0_1428
	v_ashrrev_i32_e32 v131, 31, v130
	v_cvt_pk_bf16_f32 v230, v94, v95
	v_cvt_pk_bf16_f32 v231, v96, v97

;   DEVI void operator()(int m, int n, f32x4 v) const {
;     if (m >= L) return;
;     if (n < 3072) {
;       *(u32x2*)(raw + (size_t)m * 3072 + n) = u32x2{pack2(v[0], v[1]), pack2(v[2], v[3])};
.LBB0_1432:
	s_andn2_saveexec_b64 s[10:11], s[10:11]
	s_cbranch_execz .LBB0_1434
	v_ashrrev_i32_e32 v131, 31, v130
	v_cvt_pk_bf16_f32 v232, v90, v91
	v_cvt_pk_bf16_f32 v233, v92, v93
	v_lshl_add_u64 v[226:227], v[130:131], 1, v[100:101]
	v_lshl_add_u64 v[226:227], v[226:227], 0, v[228:229]
	s_nop 0
	v_permlane16_swap_b32_e32 v230, v232
	v_permlane16_swap_b32_e32 v231, v233
	global_store_dwordx4 v[226:227], v[230:233], off
	s_nop 1

;   DEVI void operator()(int m, int n, f32x4 v) const {
;     if (m >= L) return;
;     if (n < 3072) {
;       *(u32x2*)(raw + (size_t)m * 3072 + n) = u32x2{pack2(v[0], v[1]), pack2(v[2], v[3])};
.LBB0_1438:
	s_andn2_saveexec_b64 s[10:11], s[10:11]
	s_cbranch_execz .LBB0_1440
	v_ashrrev_i32_e32 v131, 31, v130
	v_cvt_pk_bf16_f32 v230, v86, v87
	v_cvt_pk_bf16_f32 v231, v88, v89

;   DEVI void operator()(int m, int n, f32x4 v) const {
;     if (m >= L) return;
;     if (n < 3072) {
;       *(u32x2*)(raw + (size_t)m * 3072 + n) = u32x2{pack2(v[0], v[1]), pack2(v[2], v[3])};
.LBB0_1444:
	s_andn2_saveexec_b64 s[10:11], s[10:11]
	s_cbranch_execz .LBB0_1446
	v_ashrrev_i32_e32 v131, 31, v130
	v_cvt_pk_bf16_f32 v232, v82, v83
	v_cvt_pk_bf16_f32 v233, v84, v85
	v_lshl_add_u64 v[226:227], v[130:131], 1, v[100:101]
	v_lshl_add_u64 v[226:227], v[226:227], 0, v[228:229]
	s_nop 0
	v_permlane16_swap_b32_e32 v230, v232
	v_permlane16_swap_b32_e32 v231, v233
	global_store_dwordx4 v[226:227], v[230:233], off offset:64
	s_nop 1

;   DEVI void operator()(int m, int n, f32x4 v) const {
;     if (m >= L) return;
;     if (n < 3072) {
;       *(u32x2*)(raw + (size_t)m * 3072 + n) = u32x2{pack2(v[0], v[1]), pack2(v[2], v[3])};
.LBB0_1451:
	s_or_saveexec_b64 s[10:11], s[10:11]
	v_mov_b64_e32 v[86:87], s[30:31]
	s_movk_i32 s13, 0x1800
	v_mad_i64_i32 v[84:85], s[16:17], v84, s13, v[86:87]
	s_xor_b64 exec, exec, s[10:11]
	s_cbranch_execz .LBB0_1453
	v_ashrrev_i32_e32 v131, 31, v130
	v_cvt_pk_bf16_f32 v230, v78, v79
	v_cvt_pk_bf16_f32 v231, v80, v81

;   DEVI void operator()(int m, int n, f32x4 v) const {
;     if (m >= L) return;
;     if (n < 3072) {
;       *(u32x2*)(raw + (size_t)m * 3072 + n) = u32x2{pack2(v[0], v[1]), pack2(v[2], v[3])};
.LBB0_1457:
	s_andn2_saveexec_b64 s[10:11], s[10:11]
	s_cbranch_execz .LBB0_1459
	v_ashrrev_i32_e32 v131, 31, v130
	v_cvt_pk_bf16_f32 v232, v74, v75
	v_cvt_pk_bf16_f32 v233, v76, v77
	v_lshl_add_u64 v[226:227], v[130:131], 1, v[84:85]
	v_lshl_add_u64 v[226:227], v[226:227], 0, v[228:229]
	s_nop 0
	v_permlane16_swap_b32_e32 v230, v232
	v_permlane16_swap_b32_e32 v231, v233
	global_store_dwordx4 v[226:227], v[230:233], off
	s_nop 1

;   DEVI void operator()(int m, int n, f32x4 v) const {
;     if (m >= L) return;
;     if (n < 3072) {
;       *(u32x2*)(raw + (size_t)m * 3072 + n) = u32x2{pack2(v[0], v[1]), pack2(v[2], v[3])};
.LBB0_1463:
	s_andn2_saveexec_b64 s[10:11], s[10:11]
	s_cbranch_execz .LBB0_1465
	v_ashrrev_i32_e32 v131, 31, v130
	v_cvt_pk_bf16_f32 v230, v70, v71
	v_cvt_pk_bf16_f32 v231, v72, v73

;   DEVI void operator()(int m, int n, f32x4 v) const {
;     if (m >= L) return;
;     if (n < 3072) {
;       *(u32x2*)(raw + (size_t)m * 3072 + n) = u32x2{pack2(v[0], v[1]), pack2(v[2], v[3])};
.LBB0_1469:
	s_andn2_saveexec_b64 s[10:11], s[10:11]
	s_cbranch_execz .LBB0_1471
	v_ashrrev_i32_e32 v131, 31, v130
	v_cvt_pk_bf16_f32 v232, v66, v67
	v_cvt_pk_bf16_f32 v233, v68, v69
	v_lshl_add_u64 v[226:227], v[130:131], 1, v[84:85]
	v_lshl_add_u64 v[226:227], v[226:227], 0, v[228:229]
	s_nop 0
	v_permlane16_swap_b32_e32 v230, v232
	v_permlane16_swap_b32_e32 v231, v233
	global_store_dwordx4 v[226:227], v[230:233], off offset:64
	s_nop 1

;   DEVI void operator()(int m, int n, f32x4 v) const {
;     if (m >= L) return;
;     if (n < 3072) {
;       *(u32x2*)(raw + (size_t)m * 3072 + n) = u32x2{pack2(v[0], v[1]), pack2(v[2], v[3])};
.LBB0_1476:
	s_or_saveexec_b64 s[10:11], s[10:11]
	v_mov_b64_e32 v[70:71], s[30:31]
	s_movk_i32 s13, 0x1800
	v_mad_i64_i32 v[68:69], s[16:17], v68, s13, v[70:71]
	s_xor_b64 exec, exec, s[10:11]
	s_cbranch_execz .LBB0_1478
	v_ashrrev_i32_e32 v131, 31, v130
	v_cvt_pk_bf16_f32 v230, v62, v63
	v_cvt_pk_bf16_f32 v231, v64, v65

;   DEVI void operator()(int m, int n, f32x4 v) const {
;     if (m >= L) return;
;     if (n < 3072) {
;       *(u32x2*)(raw + (size_t)m * 3072 + n) = u32x2{pack2(v[0], v[1]), pack2(v[2], v[3])};
.LBB0_1482:
	s_andn2_saveexec_b64 s[10:11], s[10:11]
	s_cbranch_execz .LBB0_1484
	v_ashrrev_i32_e32 v131, 31, v130
	v_cvt_pk_bf16_f32 v232, v58, v59
	v_cvt_pk_bf16_f32 v233, v60, v61
	v_lshl_add_u64 v[226:227], v[130:131], 1, v[68:69]
	v_lshl_add_u64 v[226:227], v[226:227], 0, v[228:229]
	s_nop 0
	v_permlane16_swap_b32_e32 v230, v232
	v_permlane16_swap_b32_e32 v231, v233
	global_store_dwordx4 v[226:227], v[230:233], off
	s_nop 1

;   DEVI void operator()(int m, int n, f32x4 v) const {
;     if (m >= L) return;
;     if (n < 3072) {
;       *(u32x2*)(raw + (size_t)m * 3072 + n) = u32x2{pack2(v[0], v[1]), pack2(v[2], v[3])};
.LBB0_1488:
	s_andn2_saveexec_b64 s[10:11], s[10:11]
	s_cbranch_execz .LBB0_1490
	v_ashrrev_i32_e32 v131, 31, v130
	v_cvt_pk_bf16_f32 v230, v54, v55
	v_cvt_pk_bf16_f32 v231, v56, v57

;   DEVI void operator()(int m, int n, f32x4 v) const {
;     if (m >= L) return;
;     if (n < 3072) {
;       *(u32x2*)(raw + (size_t)m * 3072 + n) = u32x2{pack2(v[0], v[1]), pack2(v[2], v[3])};
.LBB0_1494:
	s_andn2_saveexec_b64 s[10:11], s[10:11]
	s_cbranch_execz .LBB0_1496
	v_ashrrev_i32_e32 v131, 31, v130
	v_cvt_pk_bf16_f32 v232, v50, v51
	v_cvt_pk_bf16_f32 v233, v52, v53
	v_lshl_add_u64 v[226:227], v[130:131], 1, v[68:69]
	v_lshl_add_u64 v[226:227], v[226:227], 0, v[228:229]
	s_nop 0
	v_permlane16_swap_b32_e32 v230, v232
	v_permlane16_swap_b32_e32 v231, v233
	global_store_dwordx4 v[226:227], v[230:233], off offset:64
	s_nop 1

;   DEVI void operator()(int m, int n, f32x4 v) const {
;     if (m >= L) return;
;     if (n < 3072) {
;       *(u32x2*)(raw + (size_t)m * 3072 + n) = u32x2{pack2(v[0], v[1]), pack2(v[2], v[3])};
.LBB0_1501:
	s_or_saveexec_b64 s[10:11], s[10:11]
	v_mov_b64_e32 v[54:55], s[30:31]
	s_movk_i32 s13, 0x1800
	v_mad_i64_i32 v[52:53], s[16:17], v52, s13, v[54:55]
	s_xor_b64 exec, exec, s[10:11]
	s_cbranch_execz .LBB0_1503
	v_ashrrev_i32_e32 v131, 31, v130
	v_cvt_pk_bf16_f32 v230, v46, v47
	v_cvt_pk_bf16_f32 v231, v48, v49

;   DEVI void operator()(int m, int n, f32x4 v) const {
;     if (m >= L) return;
;     if (n < 3072) {
;       *(u32x2*)(raw + (size_t)m * 3072 + n) = u32x2{pack2(v[0], v[1]), pack2(v[2], v[3])};
.LBB0_1507:
	s_andn2_saveexec_b64 s[10:11], s[10:11]
	s_cbranch_execz .LBB0_1509
	v_ashrrev_i32_e32 v131, 31, v130
	v_cvt_pk_bf16_f32 v232, v42, v43
	v_cvt_pk_bf16_f32 v233, v44, v45
	v_lshl_add_u64 v[226:227], v[130:131], 1, v[52:53]
	v_lshl_add_u64 v[226:227], v[226:227], 0, v[228:229]
	s_nop 0
	v_permlane16_swap_b32_e32 v230, v232
	v_permlane16_swap_b32_e32 v231, v233
	global_store_dwordx4 v[226:227], v[230:233], off
	s_nop 1

;   DEVI void operator()(int m, int n, f32x4 v) const {
;     if (m >= L) return;
;     if (n < 3072) {
;       *(u32x2*)(raw + (size_t)m * 3072 + n) = u32x2{pack2(v[0], v[1]), pack2(v[2], v[3])};
.LBB0_1513:
	s_andn2_saveexec_b64 s[10:11], s[10:11]
	s_cbranch_execz .LBB0_1515
	v_ashrrev_i32_e32 v131, 31, v130
	v_cvt_pk_bf16_f32 v230, v38, v39
	v_cvt_pk_bf16_f32 v231, v40, v41

;   DEVI void operator()(int m, int n, f32x4 v) const {
;     if (m >= L) return;
;     if (n < 3072) {
;       *(u32x2*)(raw + (size_t)m * 3072 + n) = u32x2{pack2(v[0], v[1]), pack2(v[2], v[3])};
.LBB0_1519:
	s_andn2_saveexec_b64 s[10:11], s[10:11]
	s_cbranch_execz .LBB0_1521
	v_ashrrev_i32_e32 v131, 31, v130
	v_cvt_pk_bf16_f32 v232, v34, v35
	v_cvt_pk_bf16_f32 v233, v36, v37
	v_lshl_add_u64 v[226:227], v[130:131], 1, v[52:53]
	v_lshl_add_u64 v[226:227], v[226:227], 0, v[228:229]
	s_nop 0
	v_permlane16_swap_b32_e32 v230, v232
	v_permlane16_swap_b32_e32 v231, v233
	global_store_dwordx4 v[226:227], v[230:233], off offset:64
	s_nop 1

;   DEVI void operator()(int m, int n, f32x4 v) const {
;     if (m >= L) return;
;     if (n < 3072) {
;       *(u32x2*)(raw + (size_t)m * 3072 + n) = u32x2{pack2(v[0], v[1]), pack2(v[2], v[3])};
.LBB0_1526:
	s_or_saveexec_b64 s[10:11], s[10:11]
	v_mov_b64_e32 v[38:39], s[30:31]
	s_movk_i32 s13, 0x1800
	v_mad_i64_i32 v[36:37], s[16:17], v36, s13, v[38:39]
	s_xor_b64 exec, exec, s[10:11]
	s_cbranch_execz .LBB0_1528
	v_ashrrev_i32_e32 v131, 31, v130
	v_cvt_pk_bf16_f32 v230, v30, v31
	v_cvt_pk_bf16_f32 v231, v32, v33

;   DEVI void operator()(int m, int n, f32x4 v) const {
;     if (m >= L) return;
;     if (n < 3072) {
;       *(u32x2*)(raw + (size_t)m * 3072 + n) = u32x2{pack2(v[0], v[1]), pack2(v[2], v[3])};
.LBB0_1532:
	s_andn2_saveexec_b64 s[10:11], s[10:11]
	s_cbranch_execz .LBB0_1534
	v_ashrrev_i32_e32 v131, 31, v130
	v_cvt_pk_bf16_f32 v232, v26, v27
	v_cvt_pk_bf16_f32 v233, v28, v29
	v_lshl_add_u64 v[226:227], v[130:131], 1, v[36:37]
	v_lshl_add_u64 v[226:227], v[226:227], 0, v[228:229]
	s_nop 0
	v_permlane16_swap_b32_e32 v230, v232
	v_permlane16_swap_b32_e32 v231, v233
	global_store_dwordx4 v[226:227], v[230:233], off
	s_nop 1

;   DEVI void operator()(int m, int n, f32x4 v) const {
;     if (m >= L) return;
;     if (n < 3072) {
;       *(u32x2*)(raw + (size_t)m * 3072 + n) = u32x2{pack2(v[0], v[1]), pack2(v[2], v[3])};
.LBB0_1538:
	s_andn2_saveexec_b64 s[10:11], s[10:11]
	s_cbranch_execz .LBB0_1540
	v_ashrrev_i32_e32 v131, 31, v130
	v_cvt_pk_bf16_f32 v230, v22, v23
	v_cvt_pk_bf16_f32 v231, v24, v25

;   DEVI void operator()(int m, int n, f32x4 v) const {
;     if (m >= L) return;
;     if (n < 3072) {
;       *(u32x2*)(raw + (size_t)m * 3072 + n) = u32x2{pack2(v[0], v[1]), pack2(v[2], v[3])};
.LBB0_1544:
	s_andn2_saveexec_b64 s[10:11], s[10:11]
	s_cbranch_execz .LBB0_1546
	v_ashrrev_i32_e32 v131, 31, v130
	v_cvt_pk_bf16_f32 v232, v18, v19
	v_cvt_pk_bf16_f32 v233, v20, v21
	v_lshl_add_u64 v[226:227], v[130:131], 1, v[36:37]
	v_lshl_add_u64 v[226:227], v[226:227], 0, v[228:229]
	s_nop 0
	v_permlane16_swap_b32_e32 v230, v232
	v_permlane16_swap_b32_e32 v231, v233
	global_store_dwordx4 v[226:227], v[230:233], off offset:64
	s_nop 1

;   DEVI void operator()(int m, int n, f32x4 v) const {
;     if (m >= L) return;
;     if (n < 3072) {
;       *(u32x2*)(raw + (size_t)m * 3072 + n) = u32x2{pack2(v[0], v[1]), pack2(v[2], v[3])};
.LBB0_1551:
	s_or_saveexec_b64 s[10:11], s[10:11]
	v_mov_b64_e32 v[22:23], s[30:31]
	s_movk_i32 s13, 0x1800
	v_mad_i64_i32 v[20:21], s[16:17], v20, s13, v[22:23]
	v_ashrrev_i32_e32 v131, 31, v130
	s_xor_b64 exec, exec, s[10:11]
	s_cbranch_execz .LBB0_1553
	v_cvt_pk_bf16_f32 v230, v14, v15
	v_cvt_pk_bf16_f32 v231, v16, v17

;   DEVI void operator()(int m, int n, f32x4 v) const {
;     if (m >= L) return;
;     if (n < 3072) {
;       *(u32x2*)(raw + (size_t)m * 3072 + n) = u32x2{pack2(v[0], v[1]), pack2(v[2], v[3])};
.LBB0_1557:
	s_andn2_saveexec_b64 s[10:11], s[10:11]
	s_cbranch_execz .LBB0_1559
	v_cvt_pk_bf16_f32 v232, v10, v11
	v_cvt_pk_bf16_f32 v233, v12, v13
	v_lshl_add_u64 v[226:227], v[130:131], 1, v[20:21]
	v_lshl_add_u64 v[226:227], v[226:227], 0, v[228:229]
	s_nop 0
	v_permlane16_swap_b32_e32 v230, v232
	v_permlane16_swap_b32_e32 v231, v233
	global_store_dwordx4 v[226:227], v[230:233], off
	s_nop 1

;   DEVI void operator()(int m, int n, f32x4 v) const {
;     if (m >= L) return;
;     if (n < 3072) {
;       *(u32x2*)(raw + (size_t)m * 3072 + n) = u32x2{pack2(v[0], v[1]), pack2(v[2], v[3])};
.LBB0_1563:
	s_andn2_saveexec_b64 s[10:11], s[10:11]
	s_cbranch_execz .LBB0_1565
	v_cvt_pk_bf16_f32 v230, v6, v7
	v_cvt_pk_bf16_f32 v231, v8, v9

;   DEVI void operator()(int m, int n, f32x4 v) const {
;     if (m >= L) return;
;     if (n < 3072) {
;       *(u32x2*)(raw + (size_t)m * 3072 + n) = u32x2{pack2(v[0], v[1]), pack2(v[2], v[3])};
.LBB0_1569:
	s_andn2_saveexec_b64 s[10:11], s[10:11]
	s_cbranch_execz .LBB0_1347
	v_cvt_pk_bf16_f32 v232, v2, v3
	v_cvt_pk_bf16_f32 v233, v4, v5
	v_lshl_add_u64 v[226:227], v[130:131], 1, v[20:21]
	v_lshl_add_u64 v[226:227], v[226:227], 0, v[228:229]
	s_nop 0
	v_permlane16_swap_b32_e32 v230, v232
	v_permlane16_swap_b32_e32 v231, v233
	global_store_dwordx4 v[226:227], v[230:233], off offset:64
	s_nop 1
	s_branch .LBB0_1347
